# attention softmax: row max / row sum across the four 16-lane rows via v_permlane16/32_swap instead of four ds_bpermute round trips
# baseline (speedup 1.0000x reference)
.LBB0_411:
	v_max_f32_e32 v5, v192, v192
	s_lshl_b32 s0, s78, 5
	v_mov_b32_e32 v4, v5
	v_add3_u32 v20, v124, s0, v127
	v_lshlrev_b32_e32 v2, 1, v2
	v_permlane16_swap_b32_e32 v5, v4
	v_add_u32_e32 v24, 0x9900, v20
	v_max_f32_e32 v4, v5, v4
	v_mov_b32_e32 v5, v4
	v_add_u32_e32 v36, v128, v2
	v_add_u32_e32 v24, 0x6800, v24
	v_permlane32_swap_b32_e32 v4, v5
	v_add_u32_e32 v28, 0x9800, v36
	v_add_u32_e32 v32, 0xb800, v36
	v_max_f32_e32 v14, v4, v5
	v_sub_f32_e32 v4, v174, v14
	v_mul_f32_e32 v4, 0x3fb8aa3b, v4
	v_sub_f32_e32 v5, v173, v14
	v_exp_f32_e32 v4, v4
	v_mul_f32_e32 v5, 0x3fb8aa3b, v5
	v_exp_f32_e32 v5, v5
	v_sub_f32_e32 v9, v177, v14
	v_add_f32_e32 v6, 0, v4
	v_mul_f32_e32 v9, 0x3fb8aa3b, v9
	v_add_f32_e32 v7, v5, v6
	v_sub_f32_e32 v6, v176, v14
	v_mul_f32_e32 v6, 0x3fb8aa3b, v6
	v_sub_f32_e32 v8, v175, v14
	v_exp_f32_e32 v46, v9
	v_sub_f32_e32 v9, v178, v14
	v_exp_f32_e32 v6, v6
	v_mul_f32_e32 v8, 0x3fb8aa3b, v8
	v_mul_f32_e32 v9, 0x3fb8aa3b, v9
	v_exp_f32_e32 v8, v8
	v_exp_f32_e32 v47, v9
	v_sub_f32_e32 v9, v183, v14
	v_mul_f32_e32 v9, 0x3fb8aa3b, v9
	v_exp_f32_e32 v173, v9
	v_sub_f32_e32 v9, v184, v14
	v_sub_f32_e32 v10, v99, v14
	v_add_f32_e32 v7, v6, v7
	v_mul_f32_e32 v9, 0x3fb8aa3b, v9
	v_sub_f32_e32 v0, v0, v14
	v_mul_f32_e32 v10, 0x3fb8aa3b, v10
	v_add_f32_e32 v7, v8, v7
	v_exp_f32_e32 v174, v9
	v_mul_f32_e32 v0, 0x3fb8aa3b, v0
	v_sub_f32_e32 v1, v1, v14
	v_exp_f32_e32 v175, v10
	v_sub_f32_e32 v10, v100, v14
	v_add_f32_e32 v7, v46, v7
	v_exp_f32_e32 v0, v0
	v_mul_f32_e32 v1, 0x3fb8aa3b, v1
	v_sub_f32_e32 v9, v98, v14
	v_mul_f32_e32 v10, 0x3fb8aa3b, v10
	v_add_f32_e32 v7, v47, v7
	v_exp_f32_e32 v1, v1
	v_mul_f32_e32 v9, 0x3fb8aa3b, v9
	v_exp_f32_e32 v176, v10
	v_sub_f32_e32 v10, v101, v14
	v_add_f32_e32 v7, v173, v7
	v_exp_f32_e32 v9, v9
	v_mul_f32_e32 v10, 0x3fb8aa3b, v10
	v_add_f32_e32 v7, v174, v7
	v_exp_f32_e32 v177, v10
	v_sub_f32_e32 v10, v102, v14
	v_add_f32_e32 v7, v0, v7
	v_mul_f32_e32 v10, 0x3fb8aa3b, v10
	v_add_f32_e32 v7, v1, v7
	v_exp_f32_e32 v178, v10
	v_sub_f32_e32 v10, v103, v14
	v_add_f32_e32 v7, v9, v7
	v_mul_f32_e32 v10, 0x3fb8aa3b, v10
	v_add_f32_e32 v7, v175, v7
	v_exp_f32_e32 v179, v10
	v_add_f32_e32 v7, v176, v7
	v_add_f32_e32 v7, v177, v7
	v_add_f32_e32 v7, v178, v7
	v_add_f32_e32 v10, v179, v7
	v_sub_f32_e32 v7, v104, v14
	v_mul_f32_e32 v7, 0x3fb8aa3b, v7
	v_sub_f32_e32 v16, v113, v14
	v_exp_f32_e32 v7, v7
	v_sub_f32_e32 v15, v106, v14
	v_mul_f32_e32 v16, 0x3fb8aa3b, v16
	v_mul_f32_e32 v15, 0x3fb8aa3b, v15
	v_exp_f32_e32 v193, v16
	v_sub_f32_e32 v16, v114, v14
	v_exp_f32_e32 v180, v15
	v_sub_f32_e32 v15, v107, v14
	v_mul_f32_e32 v16, 0x3fb8aa3b, v16
	v_mul_f32_e32 v15, 0x3fb8aa3b, v15
	v_exp_f32_e32 v114, v16
	v_sub_f32_e32 v16, v115, v14
	v_add_f32_e32 v11, v7, v10
	v_sub_f32_e32 v10, v105, v14
	v_exp_f32_e32 v181, v15
	v_sub_f32_e32 v15, v108, v14
	v_mul_f32_e32 v16, 0x3fb8aa3b, v16
	v_mul_f32_e32 v10, 0x3fb8aa3b, v10
	v_mul_f32_e32 v15, 0x3fb8aa3b, v15
	v_exp_f32_e32 v115, v16
	v_sub_f32_e32 v16, v116, v14
	v_exp_f32_e32 v10, v10
	v_exp_f32_e32 v182, v15
	v_sub_f32_e32 v15, v109, v14
	v_mul_f32_e32 v16, 0x3fb8aa3b, v16
	v_mul_f32_e32 v15, 0x3fb8aa3b, v15
	v_exp_f32_e32 v116, v16
	v_sub_f32_e32 v16, v117, v14
	v_exp_f32_e32 v183, v15
	v_sub_f32_e32 v15, v110, v14
	v_mul_f32_e32 v16, 0x3fb8aa3b, v16
	v_mul_f32_e32 v15, 0x3fb8aa3b, v15
	v_exp_f32_e32 v117, v16
	v_sub_f32_e32 v16, v118, v14
	v_add_f32_e32 v11, v10, v11
	v_exp_f32_e32 v184, v15
	v_sub_f32_e32 v15, v111, v14
	v_mul_f32_e32 v16, 0x3fb8aa3b, v16
	v_add_f32_e32 v11, v180, v11
	v_mul_f32_e32 v15, 0x3fb8aa3b, v15
	v_exp_f32_e32 v118, v16
	v_sub_f32_e32 v16, v119, v14
	v_add_f32_e32 v11, v181, v11
	v_exp_f32_e32 v192, v15
	v_mul_f32_e32 v16, 0x3fb8aa3b, v16
	v_add_f32_e32 v11, v182, v11
	v_exp_f32_e32 v119, v16
	v_sub_f32_e32 v16, v185, v14
	v_add_f32_e32 v11, v183, v11
	v_mul_f32_e32 v16, 0x3fb8aa3b, v16
	v_add_f32_e32 v11, v184, v11
	v_exp_f32_e32 v185, v16
	v_sub_f32_e32 v16, v186, v14
	v_add_f32_e32 v15, v192, v11
	v_sub_f32_e32 v11, v112, v14
	v_mul_f32_e32 v16, 0x3fb8aa3b, v16
	v_mul_f32_e32 v11, 0x3fb8aa3b, v11
	v_exp_f32_e32 v186, v16
	v_sub_f32_e32 v16, v187, v14
	v_exp_f32_e32 v11, v11
	v_mul_f32_e32 v16, 0x3fb8aa3b, v16
	v_exp_f32_e32 v187, v16
	v_sub_f32_e32 v16, v188, v14
	v_mul_f32_e32 v16, 0x3fb8aa3b, v16
	v_exp_f32_e32 v188, v16
	v_sub_f32_e32 v16, v189, v14
	v_add_f32_e32 v15, v11, v15
	v_mul_f32_e32 v16, 0x3fb8aa3b, v16
	v_add_f32_e32 v15, v193, v15
	v_exp_f32_e32 v189, v16
	v_sub_f32_e32 v16, v190, v14
	v_add_f32_e32 v15, v114, v15
	v_mul_f32_e32 v16, 0x3fb8aa3b, v16
	v_add_f32_e32 v15, v115, v15
	v_exp_f32_e32 v190, v16
	v_sub_f32_e32 v16, v191, v14
	v_add_f32_e32 v15, v116, v15
	v_mul_f32_e32 v16, 0x3fb8aa3b, v16
	v_add_f32_e32 v15, v117, v15
	v_exp_f32_e32 v191, v16
	v_sub_f32_e32 v16, v48, v14
	v_add_f32_e32 v15, v118, v15
	v_mul_f32_e32 v16, 0x3fb8aa3b, v16
	v_add_f32_e32 v15, v119, v15
	v_exp_f32_e32 v48, v16
	v_sub_f32_e32 v16, v122, v14
	v_add_f32_e32 v15, v185, v15
	v_mul_f32_e32 v16, 0x3fb8aa3b, v16
	v_add_f32_e32 v15, v186, v15
	v_exp_f32_e32 v122, v16
	v_sub_f32_e32 v16, v123, v14
	v_add_f32_e32 v15, v187, v15
	v_mul_f32_e32 v16, 0x3fb8aa3b, v16
	v_add_f32_e32 v15, v188, v15
	v_exp_f32_e32 v123, v16
	v_sub_f32_e32 v16, v120, v14
	v_add_f32_e32 v15, v189, v15
	v_mul_f32_e32 v16, 0x3fb8aa3b, v16
	v_add_f32_e32 v15, v190, v15
	v_exp_f32_e32 v120, v16
	v_sub_f32_e32 v16, v121, v14
	v_add_f32_e32 v15, v191, v15
	v_mul_f32_e32 v16, 0x3fb8aa3b, v16
	v_add_f32_e32 v15, v48, v15
	v_exp_f32_e32 v121, v16
	v_add_f32_e32 v15, v122, v15
	v_add_f32_e32 v15, v123, v15
	v_add_f32_e32 v15, v120, v15
	v_add_f32_e32 v15, v121, v15
	v_mov_b32_e32 v12, v15
	v_sub_f32_e32 v14, v57, v14
	v_mul_f32_e32 v14, 0x3fb8aa3b, v14
	v_add_u32_e32 v16, 0xb800, v20
	v_add_u32_e32 v36, 0xd800, v36
	v_permlane16_swap_b32_e32 v15, v12
	v_add_f32_e32 v12, v15, v12
	v_mov_b32_e32 v13, v12
	v_add_u32_e32 v2, v129, v2
	v_exp_f32_e32 v194, v14
	v_permlane32_swap_b32_e32 v12, v13
	ds_read2_b64 v[16:19], v16 offset0:128 offset1:132
	ds_read2_b64 v[24:27], v24 offset0:32 offset1:36
	v_add_f32_e32 v195, v12, v13
	v_add_u32_e32 v12, 0x9800, v20
	v_add_u32_e32 v20, 0xd800, v20
	ds_read2_b64 v[12:15], v12 offset0:32 offset1:36
	ds_read2_b64 v[20:23], v20 offset0:224 offset1:228
	ds_read2_b64 v[28:31], v28 offset0:32 offset1:36
	ds_read2_b64 v[32:35], v32 offset0:128 offset1:132
	ds_read2_b64 v[36:39], v36 offset0:224 offset1:228
	ds_read2_b64 v[40:43], v2 offset1:4
	v_lshlrev_b32_e32 v2, 1, v170
	v_cvt_pk_bf16_f32 v44, v4, v5
	v_add_u32_e32 v4, v128, v2
	v_cvt_pk_bf16_f32 v45, v6, v8
	v_cvt_pk_bf16_f32 v46, v46, v47
	v_cvt_pk_bf16_f32 v47, v173, v174
	v_add_u32_e32 v5, 0x9800, v4
	v_add_u32_e32 v2, v129, v2
	s_waitcnt lgkmcnt(5)
	v_mfma_f32_16x16x32_bf16 v[12:15], v[12:15], v[44:47], 0
	ds_read2_b64 v[106:109], v2 offset1:4
	v_mfma_f32_16x16x32_bf16 v[16:19], v[16:19], v[44:47], 0
	s_waitcnt lgkmcnt(5)
	v_mfma_f32_16x16x32_bf16 v[20:23], v[20:23], v[44:47], 0
	v_mfma_f32_16x16x32_bf16 v[24:27], v[24:27], v[44:47], 0
	ds_read2_b64 v[44:47], v5 offset0:32 offset1:36
	v_add_u32_e32 v5, 0xb800, v4
	v_add_u32_e32 v4, 0xd800, v4
	ds_read2_b64 v[98:101], v5 offset0:128 offset1:132
	ds_read2_b64 v[102:105], v4 offset0:224 offset1:228
	v_cvt_pk_bf16_f32 v110, v0, v1
	v_lshlrev_b32_e32 v0, 1, v171
	v_add_u32_e32 v1, v128, v0
	v_cvt_pk_bf16_f32 v111, v9, v175
	v_cvt_pk_bf16_f32 v112, v176, v177
	v_cvt_pk_bf16_f32 v113, v178, v179
	v_add_u32_e32 v2, 0x9800, v1
	v_add_u32_e32 v0, v129, v0
	s_waitcnt lgkmcnt(7)
	v_mfma_f32_16x16x32_bf16 v[12:15], v[28:31], v[110:113], v[12:15]
	ds_read2_b64 v[28:31], v2 offset0:32 offset1:36
	v_add_u32_e32 v2, 0xb800, v1
	v_add_u32_e32 v1, 0xd800, v1
	s_waitcnt lgkmcnt(7)
	v_mfma_f32_16x16x32_bf16 v[16:19], v[32:35], v[110:113], v[16:19]
	ds_read2_b64 v[32:35], v2 offset0:128 offset1:132
	s_waitcnt lgkmcnt(7)
	v_mfma_f32_16x16x32_bf16 v[20:23], v[36:39], v[110:113], v[20:23]
	ds_read2_b64 v[36:39], v1 offset0:224 offset1:228
	s_waitcnt lgkmcnt(7)
	v_mfma_f32_16x16x32_bf16 v[24:27], v[40:43], v[110:113], v[24:27]
	ds_read2_b64 v[40:43], v0 offset1:4
	v_lshlrev_b32_e32 v0, 1, v172
	v_add_u32_e32 v1, v128, v0
	v_cvt_pk_bf16_f32 v4, v7, v10
	v_cvt_pk_bf16_f32 v5, v180, v181
	v_cvt_pk_bf16_f32 v6, v182, v183
	v_cvt_pk_bf16_f32 v7, v184, v192
	v_add_u32_e32 v2, 0x9800, v1
	v_add_u32_e32 v0, v129, v0
	s_waitcnt lgkmcnt(6)
	v_mfma_f32_16x16x32_bf16 v[12:15], v[44:47], v[4:7], v[12:15]
	s_waitcnt lgkmcnt(5)
	v_mfma_f32_16x16x32_bf16 v[16:19], v[98:101], v[4:7], v[16:19]
	s_waitcnt lgkmcnt(4)
	v_mfma_f32_16x16x32_bf16 v[20:23], v[102:105], v[4:7], v[20:23]
	ds_read2_b64 v[102:105], v0 offset1:4
	v_mfma_f32_16x16x32_bf16 v[4:7], v[106:109], v[4:7], v[24:27]
	s_nop 2
	ds_read2_b64 v[24:27], v2 offset0:32 offset1:36
	v_add_u32_e32 v2, 0xb800, v1
	v_add_u32_e32 v1, 0xd800, v1
	ds_read2_b64 v[44:47], v2 offset0:128 offset1:132
	ds_read2_b64 v[98:101], v1 offset0:224 offset1:228
	v_cvt_pk_bf16_f32 v8, v11, v193
	v_cvt_pk_bf16_f32 v9, v114, v115
	v_cvt_pk_bf16_f32 v10, v116, v117
	v_cvt_pk_bf16_f32 v11, v118, v119
	v_mov_b32_e32 v2, v3
	s_waitcnt lgkmcnt(6)
	v_mfma_f32_16x16x32_bf16 v[16:19], v[32:35], v[8:11], v[16:19]
	v_add_u32_e32 v32, v128, v50
	v_add_u32_e32 v33, v129, v50
	v_mov_b32_e32 v34, v3
	v_mfma_f32_16x16x32_bf16 v[12:15], v[28:31], v[8:11], v[12:15]
	v_mov_b32_e32 v30, v3
	v_mov_b32_e32 v31, v3
	v_mov_b32_e32 v35, v3
	s_waitcnt lgkmcnt(5)
	v_mfma_f32_16x16x32_bf16 v[20:23], v[36:39], v[8:11], v[20:23]
	s_waitcnt lgkmcnt(4)
	v_mfma_f32_16x16x32_bf16 v[4:7], v[40:43], v[8:11], v[4:7]
	ds_read_b64 v[0:1], v32 offset:39680
	ds_read_b64 v[28:29], v32 offset:48640
	ds_read_b64 v[8:9], v32 offset:57600
	ds_read_b64 v[32:33], v33 offset:512
	v_mov_b32_e32 v10, v3
	v_mov_b32_e32 v11, v3
	v_cvt_pk_bf16_f32 v36, v185, v186
	v_cvt_pk_bf16_f32 v37, v187, v188
	v_cvt_pk_bf16_f32 v38, v189, v190
	v_cvt_pk_bf16_f32 v39, v191, v48
	s_waitcnt lgkmcnt(6)
	s_nop 0
	v_mfma_f32_16x16x32_bf16 v[12:15], v[24:27], v[36:39], v[12:15]
	s_waitcnt lgkmcnt(5)
	v_mfma_f32_16x16x32_bf16 v[16:19], v[44:47], v[36:39], v[16:19]
	s_waitcnt lgkmcnt(4)
	v_mfma_f32_16x16x32_bf16 v[20:23], v[98:101], v[36:39], v[20:23]
	v_mfma_f32_16x16x32_bf16 v[4:7], v[102:105], v[36:39], v[4:7]
	v_cvt_pk_bf16_f32 v24, v122, v123
	v_cvt_pk_bf16_f32 v25, v120, v121
	v_mov_b32_e32 v26, v3
	v_mov_b32_e32 v27, v3
	s_waitcnt lgkmcnt(3)
	s_nop 0
	v_mfma_f32_16x16x32_bf16 v[12:15], v[0:3], v[24:27], v[12:15]
	v_add_f32_e32 v0, v194, v195
	v_div_scale_f32 v1, s[0:1], v0, v0, 1.0
	v_rcp_f32_e32 v2, v1
	s_waitcnt lgkmcnt(1)
	v_mfma_f32_16x16x32_bf16 v[8:11], v[8:11], v[24:27], v[20:23]
	s_nop 2
	v_fma_f32 v20, -v1, v2, 1.0
	v_fmac_f32_e32 v2, v20, v2
	v_div_scale_f32 v20, vcc, 1.0, v0, 1.0
	v_mul_f32_e32 v21, v20, v2
	v_fma_f32 v22, -v1, v21, v20
	v_fmac_f32_e32 v21, v22, v2
	v_fma_f32 v1, -v1, v21, v20
	v_mfma_f32_16x16x32_bf16 v[16:19], v[28:31], v[24:27], v[16:19]
	v_div_fmas_f32 v1, v1, v2, v21
	v_div_fixup_f32 v0, v1, v0, 1.0
	v_lshlrev_b32_e32 v2, 1, v54
	s_waitcnt lgkmcnt(0)
	v_mfma_f32_16x16x32_bf16 v[4:7], v[32:35], v[24:27], v[4:7]
	v_mul_f32_e64 v12, v0, v12
	v_mul_f32_e64 v13, v0, v13
	v_pk_mul_f32 v[14:15], v[0:1], v[14:15] op_sel_hi:[0,1]
	v_lshl_add_u64 v[20:21], v[96:97], 0, v[2:3]
	v_cvt_pk_bf16_f32 v12, v12, v13
	v_cvt_pk_bf16_f32 v13, v14, v15
	global_store_dwordx2 v[20:21], v[12:13], off
	v_pk_mul_f32 v[12:13], v[0:1], v[16:17] op_sel_hi:[0,1]
	v_pk_mul_f32 v[14:15], v[0:1], v[18:19] op_sel_hi:[0,1]
	v_pk_mul_f32 v[8:9], v[0:1], v[8:9] op_sel_hi:[0,1]
	v_pk_mul_f32 v[10:11], v[0:1], v[10:11] op_sel_hi:[0,1]
	v_pk_mul_f32 v[4:5], v[0:1], v[4:5] op_sel_hi:[0,1]
	v_pk_mul_f32 v[0:1], v[0:1], v[6:7] op_sel_hi:[0,1]
	v_cvt_pk_bf16_f32 v12, v12, v13
	v_cvt_pk_bf16_f32 v13, v14, v15
	v_cvt_pk_bf16_f32 v8, v8, v9
	v_cvt_pk_bf16_f32 v9, v10, v11
	v_cvt_pk_bf16_f32 v4, v4, v5
	v_cvt_pk_bf16_f32 v5, v0, v1
	global_store_dwordx2 v[20:21], v[12:13], off offset:32
	global_store_dwordx2 v[20:21], v[8:9], off offset:64
	global_store_dwordx2 v[20:21], v[4:5], off offset:96
